# cache policy: the head-LN pass streaming loads (each row read once) marked non-temporal so they do not displace the concurrent pool-GEMM operands in L2; on top of v83
# speedup vs baseline: 1.0191x; 1.0191x over previous
; #define OPAQUE_TID() int tid = threadIdx.x; asm volatile("" : "+v"(tid)); const int lane = tid & 63, wave = __builtin_amdgcn_readfirstlane(tid >> 6); (void)lane; (void)wave
; #define YM_LOAD(row) do { const bf16_t* ur_ = U + (size_t)(row) * LDU + cbase; _Pragma("unroll") for (int hp = 0; hp < 2; ++hp) { \
;         nh[hp] = *(const u32x4*)(ur_ + C_V + 512 * hp); nz[hp] = *(const u32x4*)(ur_ + C_ZM + 512 * hp); } } while (0)
; __device__ __forceinline__ void ym_finalize(const Args& a, bool dry = false) {
;     OPAQUE_TID();
;     bf16_t* U = (bf16_t*)(a.ws + WS_U);
;     const int gw = blockIdx.x * 8 + wave, NGW = gridDim.x * 8;
;     const int cbase = (lane >> 5) * 256 + 8 * (lane & 31);
;     f32x4 gh[2][2];
; #pragma unroll
;     for (int hp = 0; hp < 2; ++hp) { gh[hp][0] = *(const f32x4*)(a.in[16] + cbase + 512 * hp); gh[hp][1] = *(const f32x4*)(a.in[16] + cbase + 512 * hp + 4); }
;     u32x4 nh[2], nz[2];
;     ...
;     if (gw < MT) YM_LOAD(gw);
;     for (int row = gw; row < MT; row += NGW) {
;         u32x4 ch[2], cz[2];
; #pragma unroll
;         for (int hp = 0; hp < 2; ++hp) { ch[hp] = nh[hp]; cz[hp] = nz[hp]; }
;         if (row + NGW < MT) YM_LOAD(row + NGW);
.LBB0_1128:
	s_or_b64 exec, exec, s[0:1]
	s_bitcmp0_b32 s2, 3
	s_cselect_b64 s[4:5], -1, 0
	s_and_b64 vcc, exec, s[4:5]
	s_waitcnt lgkmcnt(0)
	s_barrier
	s_cbranch_vccnz .LBB0_1134
	v_mov_b32_e32 v20, v180
	s_lshr_b32 s98, s2, 4
	s_sub_i32 s98, s2, s98
	s_add_i32 s98, s98, -1
	s_lshl_b32 s1, s98, 3
	s_movk_i32 s99, 0x780
	v_readfirstlane_b32 s0, v20
	s_ashr_i32 s0, s0, 6
	s_add_i32 s10, s0, s1
	s_cmp_gt_i32 s10, 0x83ff
	s_cbranch_scc1 .LBB0_1134
	v_lshlrev_b32_e32 v0, 3, v20
	s_mul_i32 s0, s10, 0x3800
	v_and_b32_e32 v8, 0x1f8, v0
	s_mul_hi_i32 s1, s10, 0x3800
	s_add_u32 s0, s28, s0
	s_addc_u32 s1, s29, s1
	v_lshlrev_b32_e32 v48, 1, v8
	v_mov_b32_e32 v49, 0
	v_lshlrev_b32_e32 v21, 2, v8
	v_lshl_add_u64 v[8:9], s[0:1], 0, v[48:49]
	s_movk_i32 s6, 0x3000
	v_add_co_u32_e32 v22, vcc, s6, v8
	s_movk_i32 s11, 0x1000
	s_nop 0
	v_addc_co_u32_e32 v23, vcc, 0, v9, vcc
	v_add_co_u32_e32 v24, vcc, s11, v8
	global_load_dwordx4 v[0:3], v21, s[20:21] offset:2048
	global_load_dwordx4 v[4:7], v21, s[20:21] offset:2064
	v_addc_co_u32_e32 v25, vcc, 0, v9, vcc
	global_load_dwordx4 v[36:39], v[24:25], off nt
	global_load_dwordx4 v[16:19], v[24:25], off offset:1024 nt
	global_load_dwordx4 v[44:47], v[22:23], off nt
	global_load_dwordx4 v[40:43], v[22:23], off offset:1024 nt
	global_load_dwordx4 v[8:11], v21, s[20:21]
	global_load_dwordx4 v[12:15], v21, s[20:21] offset:16
	v_mbcnt_hi_u32_b32 v21, -1, v181
	v_and_b32_e32 v22, 64, v21
	v_xor_b32_e32 v23, 1, v21
	v_add_u32_e32 v22, 64, v22
	v_xor_b32_e32 v24, 2, v21
	v_cmp_lt_i32_e32 vcc, v23, v22
	v_xor_b32_e32 v25, 4, v21
	v_xor_b32_e32 v26, 8, v21
	v_cndmask_b32_e32 v23, v21, v23, vcc
	v_cmp_lt_i32_e32 vcc, v24, v22
	v_xor_b32_e32 v27, 16, v21
	s_add_i32 s6, s10, s99
	v_cndmask_b32_e32 v24, v21, v24, vcc
	v_cmp_lt_i32_e32 vcc, v25, v22
	v_and_b32_e32 v20, 63, v20
	s_mul_hi_i32 s7, s6, 0x3800
	v_cndmask_b32_e32 v25, v21, v25, vcc
	v_cmp_lt_i32_e32 vcc, v26, v22
	s_mulk_i32 s6, 0x3800
	v_lshlrev_b32_e32 v48, 4, v20
	v_cndmask_b32_e32 v26, v21, v26, vcc
	v_cmp_lt_i32_e32 vcc, v27, v22
	v_lshlrev_b32_e32 v51, 2, v23
	v_lshlrev_b32_e32 v52, 2, v24
	v_cndmask_b32_e32 v21, v21, v27, vcc
	v_lshlrev_b32_e32 v53, 2, v25
	v_lshlrev_b32_e32 v54, 2, v26
	v_lshlrev_b32_e32 v55, 2, v21
	s_add_u32 s6, s28, s6
	s_mul_hi_i32 s12, s99, 0x3800
	s_mul_i32 s13, s99, 0x3800
	v_mov_b32_e32 v50, 0x358637bd
	s_mov_b32 s14, 0x800000
	s_addc_u32 s7, s29, s7
	s_waitcnt vmcnt(5)
	v_mov_b64_e32 v[28:29], v[36:37]
	s_waitcnt vmcnt(4)
	v_mov_b64_e32 v[26:27], v[18:19]
	s_waitcnt vmcnt(3)
	v_mov_b64_e32 v[20:21], v[44:45]
	s_waitcnt vmcnt(2)
	v_mov_b64_e32 v[32:33], v[40:41]
	v_mov_b64_e32 v[24:25], v[16:17]
	v_mov_b64_e32 v[30:31], v[38:39]
	v_mov_b64_e32 v[22:23], v[46:47]
	v_mov_b64_e32 v[34:35], v[42:43]
	s_branch .LBB0_1132

; #define YM_LOAD(row) do { const bf16_t* ur_ = U + (size_t)(row) * LDU + cbase; _Pragma("unroll") for (int hp = 0; hp < 2; ++hp) { \
;         nh[hp] = *(const u32x4*)(ur_ + C_V + 512 * hp); nz[hp] = *(const u32x4*)(ur_ + C_ZM + 512 * hp); } } while (0)
; __device__ __forceinline__ void ym_finalize(const Args& a, bool dry = false) {
;     ...
;     for (int row = gw; row < MT; row += NGW) {
;         u32x4 ch[2], cz[2];
; #pragma unroll
;         for (int hp = 0; hp < 2; ++hp) { ch[hp] = nh[hp]; cz[hp] = nz[hp]; }
;         if (row + NGW < MT) YM_LOAD(row + NGW);
.LBB0_1132:
	s_add_i32 s10, s10, s99
	s_cmp_gt_i32 s10, 0x83ff
	s_cselect_b64 s[8:9], -1, 0
	s_and_b64 vcc, exec, s[8:9]
	s_cbranch_vccnz .LBB0_1131
	v_lshl_add_u64 v[20:21], s[6:7], 0, v[48:49]
	v_add_co_u32_e32 v56, vcc, 0x3000, v20
	s_nop 1
	v_addc_co_u32_e32 v57, vcc, 0, v21, vcc
	v_add_co_u32_e32 v58, vcc, 0x1000, v20
	s_nop 1
	v_addc_co_u32_e32 v59, vcc, 0, v21, vcc
	global_load_dwordx4 v[20:23], v[56:57], off nt
	global_load_dwordx4 v[32:35], v[56:57], off offset:1024 nt
	global_load_dwordx4 v[28:31], v[58:59], off nt
	global_load_dwordx4 v[24:27], v[58:59], off offset:1024 nt
	s_branch .LBB0_1131

; #define OPAQUE_TID() int tid = threadIdx.x; asm volatile("" : "+v"(tid)); const int lane = tid & 63, wave = __builtin_amdgcn_readfirstlane(tid >> 6); (void)lane; (void)wave
; #define YM_LOAD(row) do { const bf16_t* ur_ = U + (size_t)(row) * LDU + cbase; _Pragma("unroll") for (int hp = 0; hp < 2; ++hp) { \
;         nh[hp] = *(const u32x4*)(ur_ + C_V + 512 * hp); nz[hp] = *(const u32x4*)(ur_ + C_ZM + 512 * hp); } } while (0)
; __device__ __forceinline__ void ym_finalize(const Args& a, bool dry = false) {
;     OPAQUE_TID();
;     bf16_t* U = (bf16_t*)(a.ws + WS_U);
;     const int gw = blockIdx.x * 8 + wave, NGW = gridDim.x * 8;
;     const int cbase = (lane >> 5) * 256 + 8 * (lane & 31);
;     f32x4 gh[2][2];
; #pragma unroll
;     for (int hp = 0; hp < 2; ++hp) { gh[hp][0] = *(const f32x4*)(a.in[16] + cbase + 512 * hp); gh[hp][1] = *(const f32x4*)(a.in[16] + cbase + 512 * hp + 4); }
;     u32x4 nh[2], nz[2];
;     ...
;     if (gw < MT) YM_LOAD(gw);
;     for (int row = gw; row < MT; row += NGW) {
;         u32x4 ch[2], cz[2];
; #pragma unroll
;         for (int hp = 0; hp < 2; ++hp) { ch[hp] = nh[hp]; cz[hp] = nz[hp]; }
;         if (row + NGW < MT) YM_LOAD(row + NGW);
.LBB0_1148:
	s_andn2_b64 vcc, exec, s[4:5]
	s_cbranch_vccnz .LBB0_1154
	s_and_b32 s98, s2, 15
	s_cmp_eq_u32 s98, 0
	s_cbranch_scc1 .LBB0_1154
	v_mov_b32_e32 v20, v180
	s_lshr_b32 s98, s2, 4
	s_sub_i32 s98, s2, s98
	s_add_i32 s98, s98, -1
	s_lshl_b32 s1, s98, 3
	s_movk_i32 s99, 0x780
	v_readfirstlane_b32 s0, v20
	s_ashr_i32 s0, s0, 6
	s_add_i32 s8, s0, s1
	s_cmp_gt_i32 s8, 0x83ff
	s_cbranch_scc1 .LBB0_1154
	v_lshlrev_b32_e32 v0, 3, v20
	s_mul_i32 s0, s8, 0x3800
	v_and_b32_e32 v8, 0x1f8, v0
	s_mul_hi_i32 s1, s8, 0x3800
	s_add_u32 s0, s28, s0
	s_addc_u32 s1, s29, s1
	v_lshlrev_b32_e32 v48, 1, v8
	v_mov_b32_e32 v49, 0
	v_lshlrev_b32_e32 v21, 2, v8
	v_lshl_add_u64 v[8:9], s[0:1], 0, v[48:49]
	s_movk_i32 s4, 0x3000
	v_add_co_u32_e32 v22, vcc, s4, v8
	s_movk_i32 s9, 0x1000
	s_nop 0
	v_addc_co_u32_e32 v23, vcc, 0, v9, vcc
	v_add_co_u32_e32 v24, vcc, s9, v8
	global_load_dwordx4 v[0:3], v21, s[20:21] offset:2048
	global_load_dwordx4 v[4:7], v21, s[20:21] offset:2064
	v_addc_co_u32_e32 v25, vcc, 0, v9, vcc
	global_load_dwordx4 v[36:39], v[24:25], off nt
	global_load_dwordx4 v[16:19], v[24:25], off offset:1024 nt
	global_load_dwordx4 v[44:47], v[22:23], off nt
	global_load_dwordx4 v[40:43], v[22:23], off offset:1024 nt
	global_load_dwordx4 v[8:11], v21, s[20:21]
	global_load_dwordx4 v[12:15], v21, s[20:21] offset:16
	v_mbcnt_hi_u32_b32 v21, -1, v181
	v_and_b32_e32 v22, 64, v21
	v_xor_b32_e32 v23, 1, v21
	v_add_u32_e32 v22, 64, v22
	v_xor_b32_e32 v24, 2, v21
	v_cmp_lt_i32_e32 vcc, v23, v22
	v_xor_b32_e32 v25, 4, v21
	v_xor_b32_e32 v26, 8, v21
	v_cndmask_b32_e32 v23, v21, v23, vcc
	v_cmp_lt_i32_e32 vcc, v24, v22
	v_xor_b32_e32 v27, 16, v21
	s_add_i32 s4, s8, s99
	v_cndmask_b32_e32 v24, v21, v24, vcc
	v_cmp_lt_i32_e32 vcc, v25, v22
	v_and_b32_e32 v20, 63, v20
	s_mul_hi_i32 s5, s4, 0x3800
	v_cndmask_b32_e32 v25, v21, v25, vcc
	v_cmp_lt_i32_e32 vcc, v26, v22
	s_mulk_i32 s4, 0x3800
	v_lshlrev_b32_e32 v48, 4, v20
	v_cndmask_b32_e32 v26, v21, v26, vcc
	v_cmp_lt_i32_e32 vcc, v27, v22
	v_lshlrev_b32_e32 v51, 2, v23
	v_lshlrev_b32_e32 v52, 2, v24
	v_cndmask_b32_e32 v21, v21, v27, vcc
	v_lshlrev_b32_e32 v53, 2, v25
	v_lshlrev_b32_e32 v54, 2, v26
	v_lshlrev_b32_e32 v55, 2, v21
	s_add_u32 s4, s28, s4
	s_mul_hi_i32 s10, s99, 0x3800
	s_mul_i32 s11, s99, 0x3800
	v_mov_b32_e32 v50, 0x358637bd
	s_mov_b32 s12, 0x800000
	s_addc_u32 s5, s29, s5
	s_waitcnt vmcnt(5)
	v_mov_b64_e32 v[28:29], v[36:37]
	s_waitcnt vmcnt(4)
	v_mov_b64_e32 v[26:27], v[18:19]
	s_waitcnt vmcnt(3)
	v_mov_b64_e32 v[20:21], v[44:45]
	s_waitcnt vmcnt(2)
	v_mov_b64_e32 v[32:33], v[40:41]
	v_mov_b64_e32 v[24:25], v[16:17]
	v_mov_b64_e32 v[30:31], v[38:39]
	v_mov_b64_e32 v[22:23], v[46:47]
	v_mov_b64_e32 v[34:35], v[42:43]
	s_branch .LBB0_1152

; #define YM_LOAD(row) do { const bf16_t* ur_ = U + (size_t)(row) * LDU + cbase; _Pragma("unroll") for (int hp = 0; hp < 2; ++hp) { \
;         nh[hp] = *(const u32x4*)(ur_ + C_V + 512 * hp); nz[hp] = *(const u32x4*)(ur_ + C_ZM + 512 * hp); } } while (0)
; __device__ __forceinline__ void ym_finalize(const Args& a, bool dry = false) {
;     ...
;     for (int row = gw; row < MT; row += NGW) {
;         u32x4 ch[2], cz[2];
; #pragma unroll
;         for (int hp = 0; hp < 2; ++hp) { ch[hp] = nh[hp]; cz[hp] = nz[hp]; }
;         if (row + NGW < MT) YM_LOAD(row + NGW);
.LBB0_1152:
	s_add_i32 s8, s8, s99
	s_cmp_gt_i32 s8, 0x83ff
	s_cselect_b64 s[6:7], -1, 0
	s_and_b64 vcc, exec, s[6:7]
	s_cbranch_vccnz .LBB0_1151
	v_lshl_add_u64 v[20:21], s[4:5], 0, v[48:49]
	v_add_co_u32_e32 v56, vcc, 0x3000, v20
	s_nop 1
	v_addc_co_u32_e32 v57, vcc, 0, v21, vcc
	v_add_co_u32_e32 v58, vcc, 0x1000, v20
	s_nop 1
	v_addc_co_u32_e32 v59, vcc, 0, v21, vcc
	global_load_dwordx4 v[20:23], v[56:57], off nt
	global_load_dwordx4 v[32:35], v[56:57], off offset:1024 nt
	global_load_dwordx4 v[28:31], v[58:59], off nt
	global_load_dwordx4 v[24:27], v[58:59], off offset:1024 nt
	s_branch .LBB0_1151
